# deferred tile boundary: vmcnt counts in the next tile's first iteration skip over the previous tile's output stores
# baseline (speedup 1.0000x reference)
; __device__ __forceinline__ unsigned cvt_pk_bf16(float lo, float hi) { unsigned r; asm volatile("v_cvt_pk_bf16_f32 %0, %1, %2" : "=v"(r) : "v"(lo), "v"(hi)); return r; }
; __device__ __forceinline__ float siluf_(float x) { return x * sigmoidf_(x); }
; #define PG8_STAGE(bufoff, gbase, voff) do { _Pragma("unroll") for (int _i = 0; _i < 2; ++_i) \
;         __builtin_amdgcn_global_load_lds((const unsigned*)((const char*)(gbase) + (voff)[_i]), (LAS unsigned*)(lds + (bufoff) + ldsw + _i * 8192), 16, 0, 0); } while (0)
; #define PG8_LDA(dst, b, h) do { _Pragma("unroll") for (int m = 0; m < 4; ++m) _Pragma("unroll") for (int k = 0; k < 2; ++k) dst[m][k] = *(const LAS bf16x8*)(lds + PG8_SA(b, h) + aoff + m * 2048 + k * 1024); } while (0)
; #define PG8_LDB(dst, b, h) do { _Pragma("unroll") for (int n = 0; n < 2; ++n) _Pragma("unroll") for (int k = 0; k < 2; ++k) dst[n][k] = *(const LAS bf16x8*)(lds + PG8_SB(b, h) + boff + n * 2048 + k * 1024); } while (0)
; #define PG8_WAIT_V(n) asm volatile("s_waitcnt vmcnt(" #n ")" ::: "memory")
; #define PG8_WAIT_L(n) asm volatile("s_waitcnt lgkmcnt(" #n ")" ::: "memory")
; #define PG8_BAR __builtin_amdgcn_s_barrier()
; #define PG8_SCHED __builtin_amdgcn_sched_barrier(0)
;     __device__ __forceinline__ void operator()(const f32x4 (&acc)[2][2][4][2], const Unit& u, int wr, int wc, int fr, int fq) const {
;     ...
;             for (int m = 0; m < 4; ++m) { const int row = row0 + ai * HALF + m * 16; bf16_t* rowp = O + (size_t)row * ldc + col0; const float rs = rsv[ai][m];
;                 f32x4 v0, v1;
; #pragma unroll
;                 for (int j = 0; j < 4; ++j) { v0[j] = siluf_(acc[ai][0][m][0][j] * rs) * (acc[ai][1][m][0][j] * rs); v1[j] = siluf_(acc[ai][0][m][1][j] * rs) * (acc[ai][1][m][1][j] * rs); }
;                 u32x4 w; w.x = cvt_pk_bf16(v0[0], v0[1]); w.y = cvt_pk_bf16(v0[2], v0[3]); w.z = cvt_pk_bf16(v1[0], v1[1]); w.w = cvt_pk_bf16(v1[2], v1[3]);
;                 *(u32x4*)rowp = w; }
; template <class Epi, bool ALIGN_EPI>
; __device__ __forceinline__ void gemm_phase(LAS unsigned char* lds, const Gemm g, const StaticOrder& S, const Epi& E, const int tid) {
;     ...
;             PG8_LDB(B0, 0, 0); PG8_LDB(B1, 0, 1); PG8_SCHED; PG8_LDA(At, 0, 0); PG8_STAGE(PG8_SA(1, 1), a1 + hA, voffA);
;             PG8_WAIT_V(8); PG8_WAIT_L(0); PG8_BAR; PG8_MMA(0, 0, At, B0); PG8_MMA(0, 1, At, B1); PG8_BAR; PG8_SCHED;
.Lgu_first_epi:
	s_add_i32 s11, s10, 2
	s_cmp_eq_u32 s58, s10
	v_lshl_add_u64 v[146:147], v[142:143], 0, s[92:93]
	s_cselect_b64 vcc, -1, 0
	v_add_u32_e32 v150, s33, v151
	s_add_i32 s10, 0, 0x14000
	v_cndmask_b32_e32 v167, v147, v139, vcc
	v_cndmask_b32_e32 v166, v146, v138, vcc
	ds_read_b128 v[146:149], v150
	ds_read_b128 v[154:157], v150 offset:1024
	ds_read_b128 v[158:161], v150 offset:2048
	ds_read_b128 v[162:165], v150 offset:3072
	v_add_u32_e32 v150, s10, v151
	ds_read_b128 v[176:179], v150
	ds_read_b128 v[180:183], v150 offset:1024
	ds_read_b128 v[184:187], v150 offset:2048
	ds_read_b128 v[188:191], v150 offset:3072
	v_cndmask_b32_e32 v221, v145, v141, vcc
	v_cndmask_b32_e32 v220, v144, v140, vcc
	v_lshl_add_u64 v[226:227], v[142:143], 0, v[134:135]
	s_add_i32 m0, s51, 0xc000
	ds_read_b128 v[192:195], v153
	ds_read_b128 v[196:199], v153 offset:1024
	ds_read_b128 v[200:203], v153 offset:2048
	ds_read_b128 v[204:207], v153 offset:3072
	ds_read_b128 v[208:211], v153 offset:4096
	ds_read_b128 v[212:215], v153 offset:5120
	ds_read_b128 v[216:219], v153 offset:6144
	ds_read_b128 v[240:243], v153 offset:7168
	global_load_lds_dwordx4 v[226:227], off
	v_lshl_add_u64 v[226:227], v[142:143], 0, v[136:137]
	s_add_i32 m0, s51, 0xe000
	s_nop 0
	global_load_lds_dwordx4 v[226:227], off
	s_waitcnt vmcnt(12)
	s_waitcnt lgkmcnt(0)
	s_barrier
	s_setprio 1
	s_waitcnt lgkmcnt(0)
	v_mfma_f32_16x16x32_bf16 v[120:123], v[146:149], v[192:195], 0
	s_lshl_b32 s98, s28, 5
	s_mov_b32 s99, 0
	s_mov_b32 s100, 0xbfb8aa3b
	s_mov_b32 s101, 0xbfb8aa3b
	v_mul_f32_e32 v56, v238, v56
	v_mul_f32_e32 v57, v238, v57
	v_mul_f32_e32 v58, v238, v58
	v_mul_f32_e32 v59, v238, v59
	v_mul_f32_e32 v60, v238, v60
	v_mul_f32_e32 v61, v238, v61
	v_mfma_f32_16x16x32_bf16 v[112:115], v[158:161], v[192:195], 0
	v_mul_f32_e32 v62, v238, v62
	v_mul_f32_e32 v63, v238, v63
	v_mul_f32_e32 v224, s100, v56
	v_mul_f32_e32 v225, s101, v57
	v_mul_f32_e32 v228, s100, v58
	v_mul_f32_e32 v229, s101, v59
	v_exp_f32_e32 v224, v224
	v_exp_f32_e32 v225, v225
	v_exp_f32_e32 v228, v228
	v_exp_f32_e32 v229, v229
	v_mfma_f32_16x16x32_bf16 v[104:107], v[146:149], v[200:203], 0
	v_add_f32_e32 v224, 1.0, v224
	v_add_f32_e32 v225, 1.0, v225
	v_add_f32_e32 v228, 1.0, v228
	v_add_f32_e32 v229, 1.0, v229
	v_rcp_f32_e32 v224, v224
	v_rcp_f32_e32 v225, v225
	v_rcp_f32_e32 v228, v228
	v_rcp_f32_e32 v229, v229
	v_nop
	v_mul_f32_e32 v56, v224, v56
	v_mfma_f32_16x16x32_bf16 v[96:99], v[158:161], v[200:203], 0
	v_mul_f32_e32 v57, v225, v57
	v_mul_f32_e32 v58, v228, v58
	v_mul_f32_e32 v59, v229, v59
	v_mul_f32_e32 v56, v60, v56
	v_mul_f32_e32 v57, v61, v57
	v_mul_f32_e32 v58, v62, v58
	v_mul_f32_e32 v59, v63, v59
	v_mul_f32_e32 v48, v238, v48
	v_mul_f32_e32 v49, v238, v49
	v_mul_f32_e32 v50, v238, v50
	v_mfma_f32_16x16x32_bf16 v[88:91], v[146:149], v[208:211], 0
	v_mul_f32_e32 v51, v238, v51
	v_mul_f32_e32 v52, v238, v52
	v_mul_f32_e32 v53, v238, v53
	v_mul_f32_e32 v54, v238, v54
	v_mul_f32_e32 v55, v238, v55
	v_mul_f32_e32 v224, s100, v48
	v_mul_f32_e32 v225, s101, v49
	v_mul_f32_e32 v228, s100, v50
	v_mul_f32_e32 v229, s101, v51
	v_exp_f32_e32 v224, v224
	v_mfma_f32_16x16x32_bf16 v[80:83], v[158:161], v[208:211], 0
	v_exp_f32_e32 v225, v225
	v_exp_f32_e32 v228, v228
	v_exp_f32_e32 v229, v229
	v_add_f32_e32 v224, 1.0, v224
	v_add_f32_e32 v225, 1.0, v225
	v_add_f32_e32 v228, 1.0, v228
	v_add_f32_e32 v229, 1.0, v229
	v_rcp_f32_e32 v224, v224
	v_rcp_f32_e32 v225, v225
	v_rcp_f32_e32 v228, v228
	v_mfma_f32_16x16x32_bf16 v[72:75], v[146:149], v[216:219], 0
	v_rcp_f32_e32 v229, v229
	v_nop
	v_mul_f32_e32 v48, v224, v48
	v_mul_f32_e32 v49, v225, v49
	v_mul_f32_e32 v50, v228, v50
	v_mul_f32_e32 v51, v229, v51
	v_mul_f32_e32 v48, v52, v48
	v_mul_f32_e32 v49, v53, v49
	v_mul_f32_e32 v50, v54, v50
	v_mul_f32_e32 v51, v55, v51
	v_mfma_f32_16x16x32_bf16 v[64:67], v[158:161], v[216:219], 0
	v_cvt_pk_bf16_f32 v56, v56, v57
	v_cvt_pk_bf16_f32 v57, v58, v59
	v_cvt_pk_bf16_f32 v58, v48, v49
	v_cvt_pk_bf16_f32 v59, v50, v51
	global_store_dwordx4 v[232:233], v[56:59], off
	v_lshl_add_u64 v[232:233], v[232:233], 0, s[98:99]
	v_mul_f32_e32 v40, v239, v40
	v_mul_f32_e32 v41, v239, v41
	v_mul_f32_e32 v42, v239, v42
	v_mul_f32_e32 v43, v239, v43
	v_mfma_f32_16x16x32_bf16 v[120:123], v[154:157], v[196:199], v[120:123]
	v_mul_f32_e32 v44, v239, v44
	v_mul_f32_e32 v45, v239, v45
	v_mul_f32_e32 v46, v239, v46
	v_mul_f32_e32 v47, v239, v47
	v_mul_f32_e32 v224, s100, v40
	v_mul_f32_e32 v225, s101, v41
	v_mul_f32_e32 v228, s100, v42
	v_mul_f32_e32 v229, s101, v43
	v_exp_f32_e32 v224, v224
	v_exp_f32_e32 v225, v225
	v_mfma_f32_16x16x32_bf16 v[112:115], v[162:165], v[196:199], v[112:115]
	v_exp_f32_e32 v228, v228
	v_exp_f32_e32 v229, v229
	v_add_f32_e32 v224, 1.0, v224
	v_add_f32_e32 v225, 1.0, v225
	v_add_f32_e32 v228, 1.0, v228
	v_add_f32_e32 v229, 1.0, v229
	v_rcp_f32_e32 v224, v224
	v_rcp_f32_e32 v225, v225
	v_rcp_f32_e32 v228, v228
	v_rcp_f32_e32 v229, v229
	v_mfma_f32_16x16x32_bf16 v[104:107], v[154:157], v[204:207], v[104:107]
	v_nop
	v_mul_f32_e32 v40, v224, v40
	v_mul_f32_e32 v41, v225, v41
	v_mul_f32_e32 v42, v228, v42
	v_mul_f32_e32 v43, v229, v43
	v_mul_f32_e32 v40, v44, v40
	v_mul_f32_e32 v41, v45, v41
	v_mul_f32_e32 v42, v46, v42
	v_mul_f32_e32 v43, v47, v43
	v_mul_f32_e32 v32, v239, v32
	v_mfma_f32_16x16x32_bf16 v[96:99], v[162:165], v[204:207], v[96:99]
	v_mul_f32_e32 v33, v239, v33
	v_mul_f32_e32 v34, v239, v34
	v_mul_f32_e32 v35, v239, v35
	v_mul_f32_e32 v36, v239, v36
	v_mul_f32_e32 v37, v239, v37
	v_mul_f32_e32 v38, v239, v38
	v_mul_f32_e32 v39, v239, v39
	v_mul_f32_e32 v224, s100, v32
	v_mul_f32_e32 v225, s101, v33
; __device__ __forceinline__ unsigned cvt_pk_bf16(float lo, float hi) { unsigned r; asm volatile("v_cvt_pk_bf16_f32 %0, %1, %2" : "=v"(r) : "v"(lo), "v"(hi)); return r; }
; __device__ __forceinline__ float siluf_(float x) { return x * sigmoidf_(x); }
; #define PG8_STAGE(bufoff, gbase, voff) do { _Pragma("unroll") for (int _i = 0; _i < 2; ++_i) \
;         __builtin_amdgcn_global_load_lds((const unsigned*)((const char*)(gbase) + (voff)[_i]), (LAS unsigned*)(lds + (bufoff) + ldsw + _i * 8192), 16, 0, 0); } while (0)
; #define PG8_LDA(dst, b, h) do { _Pragma("unroll") for (int m = 0; m < 4; ++m) _Pragma("unroll") for (int k = 0; k < 2; ++k) dst[m][k] = *(const LAS bf16x8*)(lds + PG8_SA(b, h) + aoff + m * 2048 + k * 1024); } while (0)
; #define PG8_LDB(dst, b, h) do { _Pragma("unroll") for (int n = 0; n < 2; ++n) _Pragma("unroll") for (int k = 0; k < 2; ++k) dst[n][k] = *(const LAS bf16x8*)(lds + PG8_SB(b, h) + boff + n * 2048 + k * 1024); } while (0)
;     __device__ __forceinline__ void operator()(const f32x4 (&acc)[2][2][4][2], const Unit& u, int wr, int wc, int fr, int fq) const {
;     ...
;             for (int m = 0; m < 4; ++m) { const int row = row0 + ai * HALF + m * 16; bf16_t* rowp = O + (size_t)row * ldc + col0; const float rs = rsv[ai][m];
;                 f32x4 v0, v1;
; #pragma unroll
;                 for (int j = 0; j < 4; ++j) { v0[j] = siluf_(acc[ai][0][m][0][j] * rs) * (acc[ai][1][m][0][j] * rs); v1[j] = siluf_(acc[ai][0][m][1][j] * rs) * (acc[ai][1][m][1][j] * rs); }
;                 u32x4 w; w.x = cvt_pk_bf16(v0[0], v0[1]); w.y = cvt_pk_bf16(v0[2], v0[3]); w.z = cvt_pk_bf16(v1[0], v1[1]); w.w = cvt_pk_bf16(v1[2], v1[3]);
;                 *(u32x4*)rowp = w; }
; template <class Epi, bool ALIGN_EPI>
; __device__ __forceinline__ void gemm_phase(LAS unsigned char* lds, const Gemm g, const StaticOrder& S, const Epi& E, const int tid) {
;     ...
;             PG8_LDB(B0, 0, 0); PG8_LDB(B1, 0, 1); PG8_SCHED; PG8_LDA(At, 0, 0); PG8_STAGE(PG8_SA(1, 1), a1 + hA, voffA);
;             PG8_WAIT_V(8); PG8_WAIT_L(0); PG8_BAR; PG8_MMA(0, 0, At, B0); PG8_MMA(0, 1, At, B1); PG8_BAR; PG8_SCHED;
;             PG8_LDA(At, 0, 1); PG8_STAGE(PG8_SB(0, 0), b2, voffB); PG8_STAGE(PG8_SB(0, 1), b2 + hB, voffB); PG8_STAGE(PG8_SA(0, 0), a2, voffA);
;             PG8_WAIT_V(8); PG8_WAIT_L(0); PG8_BAR; PG8_MMA(1, 0, At, B0); PG8_MMA(1, 1, At, B1); PG8_BAR; PG8_SCHED;
	v_mul_f32_e32 v228, s100, v34
	v_mfma_f32_16x16x32_bf16 v[88:91], v[154:157], v[212:215], v[88:91]
	v_mul_f32_e32 v229, s101, v35
	v_exp_f32_e32 v224, v224
	v_exp_f32_e32 v225, v225
	v_exp_f32_e32 v228, v228
	v_exp_f32_e32 v229, v229
	v_add_f32_e32 v224, 1.0, v224
	v_add_f32_e32 v225, 1.0, v225
	v_add_f32_e32 v228, 1.0, v228
	v_add_f32_e32 v229, 1.0, v229
	v_rcp_f32_e32 v224, v224
	v_mfma_f32_16x16x32_bf16 v[80:83], v[162:165], v[212:215], v[80:83]
	v_rcp_f32_e32 v225, v225
	v_rcp_f32_e32 v228, v228
	v_rcp_f32_e32 v229, v229
	v_nop
	v_mul_f32_e32 v32, v224, v32
	v_mul_f32_e32 v33, v225, v33
	v_mul_f32_e32 v34, v228, v34
	v_mul_f32_e32 v35, v229, v35
	v_mul_f32_e32 v32, v36, v32
	v_mul_f32_e32 v33, v37, v33
	v_mfma_f32_16x16x32_bf16 v[72:75], v[154:157], v[240:243], v[72:75]
	v_mul_f32_e32 v34, v38, v34
	v_mul_f32_e32 v35, v39, v35
	v_cvt_pk_bf16_f32 v40, v40, v41
	v_cvt_pk_bf16_f32 v41, v42, v43
	v_cvt_pk_bf16_f32 v42, v32, v33
	v_cvt_pk_bf16_f32 v43, v34, v35
	global_store_dwordx4 v[232:233], v[40:43], off
	v_lshl_add_u64 v[232:233], v[232:233], 0, s[98:99]
	v_mul_f32_e32 v24, v230, v24
	v_mul_f32_e32 v25, v230, v25
	v_mfma_f32_16x16x32_bf16 v[64:67], v[162:165], v[240:243], v[64:67]
	v_mul_f32_e32 v26, v230, v26
	v_mul_f32_e32 v27, v230, v27
	v_mul_f32_e32 v28, v230, v28
	v_mul_f32_e32 v29, v230, v29
	v_mul_f32_e32 v30, v230, v30
	v_mul_f32_e32 v31, v230, v31
	v_mul_f32_e32 v224, s100, v24
	v_mul_f32_e32 v225, s101, v25
	v_mul_f32_e32 v228, s100, v26
	v_mul_f32_e32 v229, s101, v27
	s_setprio 0
	s_setprio 1
	v_mfma_f32_16x16x32_bf16 v[124:127], v[176:179], v[192:195], 0
	v_exp_f32_e32 v224, v224
	v_exp_f32_e32 v225, v225
	v_exp_f32_e32 v228, v228
	v_exp_f32_e32 v229, v229
	v_add_f32_e32 v224, 1.0, v224
	v_add_f32_e32 v225, 1.0, v225
	v_add_f32_e32 v228, 1.0, v228
	v_add_f32_e32 v229, 1.0, v229
	v_rcp_f32_e32 v224, v224
	v_rcp_f32_e32 v225, v225
	v_mfma_f32_16x16x32_bf16 v[116:119], v[184:187], v[192:195], 0
	v_rcp_f32_e32 v228, v228
	v_rcp_f32_e32 v229, v229
	v_nop
	v_mul_f32_e32 v24, v224, v24
	v_mul_f32_e32 v25, v225, v25
	v_mul_f32_e32 v26, v228, v26
	v_mul_f32_e32 v27, v229, v27
	v_mul_f32_e32 v24, v28, v24
	v_mul_f32_e32 v25, v29, v25
	v_mul_f32_e32 v26, v30, v26
	v_mfma_f32_16x16x32_bf16 v[108:111], v[176:179], v[200:203], 0
	v_mul_f32_e32 v27, v31, v27
	v_mul_f32_e32 v16, v230, v16
	v_mul_f32_e32 v17, v230, v17
	v_mul_f32_e32 v18, v230, v18
	v_mul_f32_e32 v19, v230, v19
	v_mul_f32_e32 v20, v230, v20
	v_mul_f32_e32 v21, v230, v21
	v_mul_f32_e32 v22, v230, v22
	v_mul_f32_e32 v23, v230, v23
	v_mul_f32_e32 v224, s100, v16
	v_mfma_f32_16x16x32_bf16 v[100:103], v[184:187], v[200:203], 0
	v_mul_f32_e32 v225, s101, v17
	v_mul_f32_e32 v228, s100, v18
	v_mul_f32_e32 v229, s101, v19
	v_exp_f32_e32 v224, v224
	v_exp_f32_e32 v225, v225
	v_exp_f32_e32 v228, v228
	v_exp_f32_e32 v229, v229
	v_add_f32_e32 v224, 1.0, v224
	v_add_f32_e32 v225, 1.0, v225
	v_add_f32_e32 v228, 1.0, v228
	v_mfma_f32_16x16x32_bf16 v[92:95], v[176:179], v[208:211], 0
	v_add_f32_e32 v229, 1.0, v229
	v_rcp_f32_e32 v224, v224
	v_rcp_f32_e32 v225, v225
	v_rcp_f32_e32 v228, v228
	v_rcp_f32_e32 v229, v229
	v_nop
	v_mul_f32_e32 v16, v224, v16
	v_mul_f32_e32 v17, v225, v17
	v_mul_f32_e32 v18, v228, v18
	v_mul_f32_e32 v19, v229, v19
	v_mfma_f32_16x16x32_bf16 v[84:87], v[184:187], v[208:211], 0
	v_mul_f32_e32 v16, v20, v16
	v_mul_f32_e32 v17, v21, v17
	v_mul_f32_e32 v18, v22, v18
	v_mul_f32_e32 v19, v23, v19
	v_cvt_pk_bf16_f32 v24, v24, v25
	v_cvt_pk_bf16_f32 v25, v26, v27
	v_cvt_pk_bf16_f32 v26, v16, v17
	v_cvt_pk_bf16_f32 v27, v18, v19
	global_store_dwordx4 v[232:233], v[24:27], off
	v_lshl_add_u64 v[232:233], v[232:233], 0, s[98:99]
	v_mfma_f32_16x16x32_bf16 v[76:79], v[176:179], v[216:219], 0
	v_mul_f32_e32 v8, v231, v8
	v_mul_f32_e32 v9, v231, v9
	v_mul_f32_e32 v10, v231, v10
	v_mul_f32_e32 v11, v231, v11
	v_mul_f32_e32 v12, v231, v12
	v_mul_f32_e32 v13, v231, v13
	v_mul_f32_e32 v14, v231, v14
	v_mul_f32_e32 v15, v231, v15
	v_mul_f32_e32 v224, s100, v8
	v_mul_f32_e32 v225, s101, v9
	v_mfma_f32_16x16x32_bf16 v[68:71], v[184:187], v[216:219], 0
	v_mul_f32_e32 v228, s100, v10
	v_mul_f32_e32 v229, s101, v11
	v_exp_f32_e32 v224, v224
	v_exp_f32_e32 v225, v225
	v_exp_f32_e32 v228, v228
	v_exp_f32_e32 v229, v229
	v_add_f32_e32 v224, 1.0, v224
	v_add_f32_e32 v225, 1.0, v225
	v_add_f32_e32 v228, 1.0, v228
	v_add_f32_e32 v229, 1.0, v229
	v_mfma_f32_16x16x32_bf16 v[124:127], v[180:183], v[196:199], v[124:127]
	v_rcp_f32_e32 v224, v224
	v_rcp_f32_e32 v225, v225
	v_rcp_f32_e32 v228, v228
	v_rcp_f32_e32 v229, v229
	v_nop
	v_mul_f32_e32 v8, v224, v8
	v_mul_f32_e32 v9, v225, v9
	v_mul_f32_e32 v10, v228, v10
	v_mul_f32_e32 v11, v229, v11
	v_mul_f32_e32 v8, v12, v8
	v_mfma_f32_16x16x32_bf16 v[116:119], v[188:191], v[196:199], v[116:119]
	v_mul_f32_e32 v9, v13, v9
	v_mul_f32_e32 v10, v14, v10
	v_mul_f32_e32 v11, v15, v11
	v_mul_f32_e32 v4, v231, v4
	v_mul_f32_e32 v5, v231, v5
	v_mul_f32_e32 v6, v231, v6
	v_mul_f32_e32 v7, v231, v7
	v_mul_f32_e32 v0, v231, v0
	v_mul_f32_e32 v1, v231, v1
	v_mul_f32_e32 v2, v231, v2
	v_mfma_f32_16x16x32_bf16 v[108:111], v[180:183], v[204:207], v[108:111]
	v_mul_f32_e32 v3, v231, v3
	v_mul_f32_e32 v224, s100, v4
	v_mul_f32_e32 v225, s101, v5
	v_mul_f32_e32 v228, s100, v6
	v_mul_f32_e32 v229, s101, v7
	v_exp_f32_e32 v224, v224
	v_exp_f32_e32 v225, v225
	v_exp_f32_e32 v228, v228
	v_exp_f32_e32 v229, v229
	v_add_f32_e32 v224, 1.0, v224
	v_mfma_f32_16x16x32_bf16 v[100:103], v[188:191], v[204:207], v[100:103]
	v_add_f32_e32 v225, 1.0, v225
	v_add_f32_e32 v228, 1.0, v228
	v_add_f32_e32 v229, 1.0, v229
	v_rcp_f32_e32 v224, v224
	v_rcp_f32_e32 v225, v225
	v_rcp_f32_e32 v228, v228
	v_rcp_f32_e32 v229, v229
	v_nop
	v_mul_f32_e32 v4, v224, v4
	v_mul_f32_e32 v5, v225, v5
	v_mfma_f32_16x16x32_bf16 v[92:95], v[180:183], v[212:215], v[92:95]
	v_mul_f32_e32 v6, v228, v6
	v_mul_f32_e32 v7, v229, v7
	v_mul_f32_e32 v4, v0, v4
	v_mul_f32_e32 v5, v1, v5
	v_mul_f32_e32 v6, v2, v6
	v_mul_f32_e32 v7, v3, v7
	v_cvt_pk_bf16_f32 v8, v8, v9
	v_cvt_pk_bf16_f32 v9, v10, v11
	v_cvt_pk_bf16_f32 v10, v4, v5
	v_cvt_pk_bf16_f32 v11, v6, v7
	v_mfma_f32_16x16x32_bf16 v[84:87], v[188:191], v[212:215], v[84:87]
	global_store_dwordx4 v[232:233], v[8:11], off
	v_mfma_f32_16x16x32_bf16 v[76:79], v[180:183], v[240:243], v[76:79]
	v_mfma_f32_16x16x32_bf16 v[68:71], v[188:191], v[240:243], v[68:71]
	s_setprio 0
	s_barrier
; #define PG8_STAGE(bufoff, gbase, voff) do { _Pragma("unroll") for (int _i = 0; _i < 2; ++_i) \
;         __builtin_amdgcn_global_load_lds((const unsigned*)((const char*)(gbase) + (voff)[_i]), (LAS unsigned*)(lds + (bufoff) + ldsw + _i * 8192), 16, 0, 0); } while (0)
; #define PG8_LDA(dst, b, h) do { _Pragma("unroll") for (int m = 0; m < 4; ++m) _Pragma("unroll") for (int k = 0; k < 2; ++k) dst[m][k] = *(const LAS bf16x8*)(lds + PG8_SA(b, h) + aoff + m * 2048 + k * 1024); } while (0)
; #define PG8_LDB(dst, b, h) do { _Pragma("unroll") for (int n = 0; n < 2; ++n) _Pragma("unroll") for (int k = 0; k < 2; ++k) dst[n][k] = *(const LAS bf16x8*)(lds + PG8_SB(b, h) + boff + n * 2048 + k * 1024); } while (0)
; #define PG8_MMA(ai, bj, At, Bt) do { __builtin_amdgcn_s_setprio(1); _Pragma("unroll") for (int k = 0; k < 2; ++k) _Pragma("unroll") for (int m = 0; m < 4; ++m) _Pragma("unroll") for (int n = 0; n < 2; ++n) \
;         acc[ai][bj][m][n] = __builtin_amdgcn_mfma_f32_16x16x32_bf16(Bt[n][k], At[m][k], acc[ai][bj][m][n], 0, 0, 0); __builtin_amdgcn_s_setprio(0); } while (0)
; #define PG8_WAIT_V(n) asm volatile("s_waitcnt vmcnt(" #n ")" ::: "memory")
; #define PG8_WAIT_L(n) asm volatile("s_waitcnt lgkmcnt(" #n ")" ::: "memory")
; #define PG8_BAR __builtin_amdgcn_s_barrier()
; #define PG8_SCHED __builtin_amdgcn_sched_barrier(0)
; template <class Epi, bool ALIGN_EPI>
; __device__ __forceinline__ void gemm_phase(LAS unsigned char* lds, const Gemm g, const StaticOrder& S, const Epi& E, const int tid) {
;     ...
;             PG8_LDA(At, 0, 1); PG8_STAGE(PG8_SB(0, 0), b2, voffB); PG8_STAGE(PG8_SB(0, 1), b2 + hB, voffB); PG8_STAGE(PG8_SA(0, 0), a2, voffA);
;             PG8_WAIT_V(8); PG8_WAIT_L(0); PG8_BAR; PG8_MMA(1, 0, At, B0); PG8_MMA(1, 1, At, B1); PG8_BAR; PG8_SCHED;
;             PG8_LDB(B0, 1, 0); PG8_LDB(B1, 1, 1); PG8_SCHED; PG8_LDA(At, 1, 0); PG8_STAGE(PG8_SA(0, 1), a2 + hA, voffA);
;             PG8_WAIT_V(8); PG8_WAIT_L(0); PG8_BAR; PG8_MMA(0, 0, At, B0); PG8_MMA(0, 1, At, B1); PG8_BAR; PG8_SCHED;
	s_add_i32 s65, s33, s45
	v_lshl_add_u64 v[226:227], v[220:221], 0, v[168:169]
	s_mov_b32 m0, s65
	ds_read_b128 v[192:195], v153 offset:16384
	ds_read_b128 v[196:199], v153 offset:17408
	ds_read_b128 v[200:203], v153 offset:18432
	ds_read_b128 v[204:207], v153 offset:19456
	ds_read_b128 v[208:211], v153 offset:20480
	ds_read_b128 v[212:215], v153 offset:21504
	ds_read_b128 v[216:219], v153 offset:22528
	ds_read_b128 v[240:243], v153 offset:23552
	global_load_lds_dwordx4 v[226:227], off
	v_lshl_add_u64 v[244:245], v[220:221], 0, v[128:129]
	s_add_i32 m0, s65, 0x2000
	v_lshl_add_u64 v[220:221], v[220:221], 0, s[12:13]
	s_add_i32 s10, s10, s45
	global_load_lds_dwordx4 v[244:245], off
	v_lshl_add_u64 v[246:247], v[220:221], 0, v[168:169]
	s_mov_b32 m0, s10
	v_lshl_add_u64 v[220:221], v[220:221], 0, v[128:129]
	global_load_lds_dwordx4 v[246:247], off
	s_add_i32 m0, s10, 0x2000
	v_lshl_add_u64 v[248:249], v[166:167], 0, v[132:133]
	global_load_lds_dwordx4 v[220:221], off
	s_mov_b32 m0, s51
	v_lshl_add_u64 v[250:251], v[166:167], 0, v[130:131]
	global_load_lds_dwordx4 v[248:249], off
	s_mov_b32 m0, s52
	s_nop 0
	global_load_lds_dwordx4 v[250:251], off
	s_waitcnt vmcnt(16)
	s_waitcnt lgkmcnt(0)
	s_barrier
	s_setprio 1
	s_waitcnt lgkmcnt(0)
	v_mfma_f32_16x16x32_bf16 v[56:59], v[146:149], v[192:195], 0
	v_mfma_f32_16x16x32_bf16 v[48:51], v[158:161], v[192:195], 0
	v_mfma_f32_16x16x32_bf16 v[40:43], v[146:149], v[200:203], 0
	v_mfma_f32_16x16x32_bf16 v[32:35], v[158:161], v[200:203], 0
	v_mfma_f32_16x16x32_bf16 v[24:27], v[146:149], v[208:211], 0
	v_mfma_f32_16x16x32_bf16 v[16:19], v[158:161], v[208:211], 0
	v_mfma_f32_16x16x32_bf16 v[8:11], v[146:149], v[216:219], 0
	v_mfma_f32_16x16x32_bf16 v[4:7], v[158:161], v[216:219], 0
	v_mfma_f32_16x16x32_bf16 v[56:59], v[154:157], v[196:199], v[56:59]
	v_mfma_f32_16x16x32_bf16 v[48:51], v[162:165], v[196:199], v[48:51]
	v_mfma_f32_16x16x32_bf16 v[40:43], v[154:157], v[204:207], v[40:43]
	v_mfma_f32_16x16x32_bf16 v[32:35], v[162:165], v[204:207], v[32:35]
	v_mfma_f32_16x16x32_bf16 v[24:27], v[154:157], v[212:215], v[24:27]
	v_mfma_f32_16x16x32_bf16 v[16:19], v[162:165], v[212:215], v[16:19]
	v_mfma_f32_16x16x32_bf16 v[8:11], v[154:157], v[240:243], v[8:11]
	v_mfma_f32_16x16x32_bf16 v[4:7], v[162:165], v[240:243], v[4:7]
	s_setprio 0
	s_setprio 1
	v_mfma_f32_16x16x32_bf16 v[60:63], v[176:179], v[192:195], 0
	v_mfma_f32_16x16x32_bf16 v[52:55], v[184:187], v[192:195], 0
	v_mfma_f32_16x16x32_bf16 v[44:47], v[176:179], v[200:203], 0
	v_mfma_f32_16x16x32_bf16 v[36:39], v[184:187], v[200:203], 0
	v_mfma_f32_16x16x32_bf16 v[28:31], v[176:179], v[208:211], 0
	v_mfma_f32_16x16x32_bf16 v[20:23], v[184:187], v[208:211], 0
	v_mfma_f32_16x16x32_bf16 v[12:15], v[176:179], v[216:219], 0
	v_mfma_f32_16x16x32_bf16 v[0:3], v[184:187], v[216:219], 0
	v_mfma_f32_16x16x32_bf16 v[60:63], v[180:183], v[196:199], v[60:63]
	v_mfma_f32_16x16x32_bf16 v[52:55], v[188:191], v[196:199], v[52:55]
	v_mfma_f32_16x16x32_bf16 v[44:47], v[180:183], v[204:207], v[44:47]
	v_mfma_f32_16x16x32_bf16 v[36:39], v[188:191], v[204:207], v[36:39]
	v_mfma_f32_16x16x32_bf16 v[28:31], v[180:183], v[212:215], v[28:31]
	v_mfma_f32_16x16x32_bf16 v[20:23], v[188:191], v[212:215], v[20:23]
	v_mfma_f32_16x16x32_bf16 v[12:15], v[180:183], v[240:243], v[12:15]
	v_mfma_f32_16x16x32_bf16 v[0:3], v[188:191], v[240:243], v[0:3]
	s_setprio 0
	s_barrier
	s_add_i32 s10, 0, 0x18000
	v_add_u32_e32 v150, s10, v151
	s_add_i32 s65, 0, 0x1c000
	ds_read_b128 v[146:149], v150
	ds_read_b128 v[154:157], v150 offset:1024
	ds_read_b128 v[158:161], v150 offset:2048
	ds_read_b128 v[162:165], v150 offset:3072
	v_add_u32_e32 v150, s65, v151
	ds_read_b128 v[176:179], v150
	ds_read_b128 v[180:183], v150 offset:1024
	ds_read_b128 v[184:187], v150 offset:2048
	ds_read_b128 v[188:191], v150 offset:3072
	v_lshl_add_u64 v[166:167], v[166:167], 0, s[94:95]
	s_mov_b32 m0, s53
	v_lshl_add_u64 v[252:253], v[166:167], 0, v[132:133]
	ds_read_b128 v[192:195], v153 offset:32768
	ds_read_b128 v[196:199], v153 offset:33792
	ds_read_b128 v[200:203], v153 offset:34816
	ds_read_b128 v[204:207], v153 offset:35840
	ds_read_b128 v[208:211], v153 offset:36864
	ds_read_b128 v[212:215], v153 offset:37888
	ds_read_b128 v[216:219], v153 offset:38912
	ds_read_b128 v[240:243], v153 offset:39936
	global_load_lds_dwordx4 v[252:253], off
	v_lshl_add_u64 v[166:167], v[166:167], 0, v[130:131]
	s_mov_b32 m0, s54
	s_nop 0
	global_load_lds_dwordx4 v[166:167], off
	s_waitcnt vmcnt(12)
	s_waitcnt lgkmcnt(0)
	s_barrier
; #define PG8_STAGE(bufoff, gbase, voff) do { _Pragma("unroll") for (int _i = 0; _i < 2; ++_i) \
;         __builtin_amdgcn_global_load_lds((const unsigned*)((const char*)(gbase) + (voff)[_i]), (LAS unsigned*)(lds + (bufoff) + ldsw + _i * 8192), 16, 0, 0); } while (0)
; #define PG8_LDA(dst, b, h) do { _Pragma("unroll") for (int m = 0; m < 4; ++m) _Pragma("unroll") for (int k = 0; k < 2; ++k) dst[m][k] = *(const LAS bf16x8*)(lds + PG8_SA(b, h) + aoff + m * 2048 + k * 1024); } while (0)
; #define PG8_MMA(ai, bj, At, Bt) do { __builtin_amdgcn_s_setprio(1); _Pragma("unroll") for (int k = 0; k < 2; ++k) _Pragma("unroll") for (int m = 0; m < 4; ++m) _Pragma("unroll") for (int n = 0; n < 2; ++n) \
;         acc[ai][bj][m][n] = __builtin_amdgcn_mfma_f32_16x16x32_bf16(Bt[n][k], At[m][k], acc[ai][bj][m][n], 0, 0, 0); __builtin_amdgcn_s_setprio(0); } while (0)
; #define PG8_WAIT_V(n) asm volatile("s_waitcnt vmcnt(" #n ")" ::: "memory")
; #define PG8_WAIT_L(n) asm volatile("s_waitcnt lgkmcnt(" #n ")" ::: "memory")
; #define PG8_BAR __builtin_amdgcn_s_barrier()
; #define PG8_SCHED __builtin_amdgcn_sched_barrier(0)
; template <class Epi, bool ALIGN_EPI>
; __device__ __forceinline__ void gemm_phase(LAS unsigned char* lds, const Gemm g, const StaticOrder& S, const Epi& E, const int tid) {
;     ...
;             PG8_WAIT_V(8); PG8_WAIT_L(0); PG8_BAR; PG8_MMA(0, 0, At, B0); PG8_MMA(0, 1, At, B1); PG8_BAR; PG8_SCHED;
;             PG8_LDA(At, 1, 1); PG8_STAGE(PG8_SB(1, 0), b3, voffB); PG8_STAGE(PG8_SB(1, 1), b3 + hB, voffB); PG8_STAGE(PG8_SA(1, 0), a3, voffA);
;             PG8_WAIT_V(8); PG8_WAIT_L(0); PG8_BAR; PG8_MMA(1, 0, At, B0); PG8_MMA(1, 1, At, B1); PG8_BAR; PG8_SCHED;
;         }
	s_setprio 1
	s_waitcnt lgkmcnt(0)
	v_mfma_f32_16x16x32_bf16 v[120:123], v[146:149], v[192:195], v[120:123]
	v_mfma_f32_16x16x32_bf16 v[112:115], v[158:161], v[192:195], v[112:115]
	v_mfma_f32_16x16x32_bf16 v[104:107], v[146:149], v[200:203], v[104:107]
	v_mfma_f32_16x16x32_bf16 v[96:99], v[158:161], v[200:203], v[96:99]
	v_mfma_f32_16x16x32_bf16 v[88:91], v[146:149], v[208:211], v[88:91]
	v_mfma_f32_16x16x32_bf16 v[80:83], v[158:161], v[208:211], v[80:83]
	v_mfma_f32_16x16x32_bf16 v[72:75], v[146:149], v[216:219], v[72:75]
	v_mfma_f32_16x16x32_bf16 v[64:67], v[158:161], v[216:219], v[64:67]
	v_mfma_f32_16x16x32_bf16 v[120:123], v[154:157], v[196:199], v[120:123]
	v_mfma_f32_16x16x32_bf16 v[112:115], v[162:165], v[196:199], v[112:115]
	v_mfma_f32_16x16x32_bf16 v[104:107], v[154:157], v[204:207], v[104:107]
	v_mfma_f32_16x16x32_bf16 v[96:99], v[162:165], v[204:207], v[96:99]
	v_mfma_f32_16x16x32_bf16 v[88:91], v[154:157], v[212:215], v[88:91]
	v_mfma_f32_16x16x32_bf16 v[80:83], v[162:165], v[212:215], v[80:83]
	v_mfma_f32_16x16x32_bf16 v[72:75], v[154:157], v[240:243], v[72:75]
	v_mfma_f32_16x16x32_bf16 v[64:67], v[162:165], v[240:243], v[64:67]
	s_setprio 0
	s_setprio 1
	v_mfma_f32_16x16x32_bf16 v[124:127], v[176:179], v[192:195], v[124:127]
	v_mfma_f32_16x16x32_bf16 v[116:119], v[184:187], v[192:195], v[116:119]
	v_mfma_f32_16x16x32_bf16 v[108:111], v[176:179], v[200:203], v[108:111]
	v_mfma_f32_16x16x32_bf16 v[100:103], v[184:187], v[200:203], v[100:103]
	v_mfma_f32_16x16x32_bf16 v[92:95], v[176:179], v[208:211], v[92:95]
	v_mfma_f32_16x16x32_bf16 v[84:87], v[184:187], v[208:211], v[84:87]
	v_mfma_f32_16x16x32_bf16 v[76:79], v[176:179], v[216:219], v[76:79]
	v_mfma_f32_16x16x32_bf16 v[68:71], v[184:187], v[216:219], v[68:71]
	v_mfma_f32_16x16x32_bf16 v[124:127], v[180:183], v[196:199], v[124:127]
	v_mfma_f32_16x16x32_bf16 v[116:119], v[188:191], v[196:199], v[116:119]
	v_mfma_f32_16x16x32_bf16 v[108:111], v[180:183], v[204:207], v[108:111]
	v_mfma_f32_16x16x32_bf16 v[100:103], v[188:191], v[204:207], v[100:103]
	v_mfma_f32_16x16x32_bf16 v[92:95], v[180:183], v[212:215], v[92:95]
	v_mfma_f32_16x16x32_bf16 v[84:87], v[188:191], v[212:215], v[84:87]
	v_mfma_f32_16x16x32_bf16 v[76:79], v[180:183], v[240:243], v[76:79]
	v_mfma_f32_16x16x32_bf16 v[68:71], v[188:191], v[240:243], v[68:71]
	s_setprio 0
	s_barrier
	s_add_i32 s10, s10, s45
	v_lshl_add_u64 v[166:167], v[226:227], 0, s[92:93]
	s_mov_b32 m0, s10
	ds_read_b128 v[192:195], v153 offset:49152
	ds_read_b128 v[196:199], v153 offset:50176
	ds_read_b128 v[200:203], v153 offset:51200
	ds_read_b128 v[204:207], v153 offset:52224
	ds_read_b128 v[208:211], v153 offset:53248
	ds_read_b128 v[212:215], v153 offset:54272
	ds_read_b128 v[216:219], v153 offset:55296
	ds_read_b128 v[240:243], v153 offset:56320
	global_load_lds_dwordx4 v[166:167], off
	v_lshl_add_u64 v[166:167], v[244:245], 0, s[92:93]
	s_add_i32 m0, s10, 0x2000
	s_add_i32 s10, s65, s45
	global_load_lds_dwordx4 v[166:167], off
	v_lshl_add_u64 v[166:167], v[246:247], 0, s[92:93]
	s_mov_b32 m0, s10
	s_nop 0
	global_load_lds_dwordx4 v[166:167], off
	v_lshl_add_u64 v[166:167], v[220:221], 0, s[92:93]
	s_add_i32 m0, s10, 0x2000
	s_nop 0
	global_load_lds_dwordx4 v[166:167], off
	v_lshl_add_u64 v[166:167], v[248:249], 0, s[92:93]
	s_mov_b32 m0, s56
	s_nop 0
	global_load_lds_dwordx4 v[166:167], off
	v_lshl_add_u64 v[166:167], v[250:251], 0, s[92:93]
	s_mov_b32 m0, s57
	s_nop 0
	global_load_lds_dwordx4 v[166:167], off
	s_waitcnt vmcnt(8)
	s_waitcnt lgkmcnt(0)
	s_barrier
	s_setprio 1
	s_waitcnt lgkmcnt(0)
	v_mfma_f32_16x16x32_bf16 v[56:59], v[146:149], v[192:195], v[56:59]
	v_mfma_f32_16x16x32_bf16 v[48:51], v[158:161], v[192:195], v[48:51]
	v_mfma_f32_16x16x32_bf16 v[40:43], v[146:149], v[200:203], v[40:43]
	v_mfma_f32_16x16x32_bf16 v[32:35], v[158:161], v[200:203], v[32:35]
	v_mfma_f32_16x16x32_bf16 v[24:27], v[146:149], v[208:211], v[24:27]
	v_mfma_f32_16x16x32_bf16 v[16:19], v[158:161], v[208:211], v[16:19]
	v_mfma_f32_16x16x32_bf16 v[8:11], v[146:149], v[216:219], v[8:11]
	v_mfma_f32_16x16x32_bf16 v[4:7], v[158:161], v[216:219], v[4:7]
	v_mfma_f32_16x16x32_bf16 v[56:59], v[154:157], v[196:199], v[56:59]
	v_mfma_f32_16x16x32_bf16 v[48:51], v[162:165], v[196:199], v[48:51]
	v_mfma_f32_16x16x32_bf16 v[40:43], v[154:157], v[204:207], v[40:43]
	v_mfma_f32_16x16x32_bf16 v[32:35], v[162:165], v[204:207], v[32:35]
	v_mfma_f32_16x16x32_bf16 v[24:27], v[154:157], v[212:215], v[24:27]
	v_mfma_f32_16x16x32_bf16 v[16:19], v[162:165], v[212:215], v[16:19]
	v_mfma_f32_16x16x32_bf16 v[8:11], v[154:157], v[240:243], v[8:11]
	v_mfma_f32_16x16x32_bf16 v[4:7], v[162:165], v[240:243], v[4:7]
	s_setprio 0
	s_setprio 1
	v_mfma_f32_16x16x32_bf16 v[60:63], v[176:179], v[192:195], v[60:63]
	v_mfma_f32_16x16x32_bf16 v[52:55], v[184:187], v[192:195], v[52:55]
	v_mfma_f32_16x16x32_bf16 v[44:47], v[176:179], v[200:203], v[44:47]
	v_mfma_f32_16x16x32_bf16 v[36:39], v[184:187], v[200:203], v[36:39]
	v_mfma_f32_16x16x32_bf16 v[28:31], v[176:179], v[208:211], v[28:31]
	v_mfma_f32_16x16x32_bf16 v[20:23], v[184:187], v[208:211], v[20:23]
	v_mfma_f32_16x16x32_bf16 v[12:15], v[176:179], v[216:219], v[12:15]
	v_mfma_f32_16x16x32_bf16 v[0:3], v[184:187], v[216:219], v[0:3]
	v_mfma_f32_16x16x32_bf16 v[60:63], v[180:183], v[196:199], v[60:63]
	v_mfma_f32_16x16x32_bf16 v[52:55], v[188:191], v[196:199], v[52:55]
	v_mfma_f32_16x16x32_bf16 v[44:47], v[180:183], v[204:207], v[44:47]
	v_mfma_f32_16x16x32_bf16 v[36:39], v[188:191], v[204:207], v[36:39]
	v_mfma_f32_16x16x32_bf16 v[28:31], v[180:183], v[212:215], v[28:31]
	v_mfma_f32_16x16x32_bf16 v[20:23], v[188:191], v[212:215], v[20:23]
	v_mfma_f32_16x16x32_bf16 v[12:15], v[180:183], v[240:243], v[12:15]
	v_mfma_f32_16x16x32_bf16 v[0:3], v[188:191], v[240:243], v[0:3]
	s_setprio 0
	s_barrier
	v_lshl_add_u64 v[142:143], v[142:143], 0, s[80:81]
	v_lshl_add_u64 v[144:145], v[144:145], 0, s[80:81]
	s_mov_b32 s10, s11
	s_cmp_eq_u32 s10, s58
	s_cbranch_scc1 .Lgu_last
	s_branch .LBB0_308

; __device__ __forceinline__ unsigned cvt_pk_bf16(float lo, float hi) { unsigned r; asm volatile("v_cvt_pk_bf16_f32 %0, %1, %2" : "=v"(r) : "v"(lo), "v"(hi)); return r; }
; __device__ __forceinline__ float gelu_tanh(float x) { const float u = 0.7978845608028654f * (x + 0.044715f * x * x * x); return x * fast_rcp(1.0f + fast_exp2(-2.0f * LOG2E * u)); }
; #define PG8_STAGE(bufoff, gbase, voff) do { _Pragma("unroll") for (int _i = 0; _i < 2; ++_i) \
;         __builtin_amdgcn_global_load_lds((const unsigned*)((const char*)(gbase) + (voff)[_i]), (LAS unsigned*)(lds + (bufoff) + ldsw + _i * 8192), 16, 0, 0); } while (0)
; #define PG8_LDA(dst, b, h) do { _Pragma("unroll") for (int m = 0; m < 4; ++m) _Pragma("unroll") for (int k = 0; k < 2; ++k) dst[m][k] = *(const LAS bf16x8*)(lds + PG8_SA(b, h) + aoff + m * 2048 + k * 1024); } while (0)
; #define PG8_LDB(dst, b, h) do { _Pragma("unroll") for (int n = 0; n < 2; ++n) _Pragma("unroll") for (int k = 0; k < 2; ++k) dst[n][k] = *(const LAS bf16x8*)(lds + PG8_SB(b, h) + boff + n * 2048 + k * 1024); } while (0)
; #define PG8_WAIT_V(n) asm volatile("s_waitcnt vmcnt(" #n ")" ::: "memory")
;     __device__ __forceinline__ void operator()(const f32x4 (&acc)[2][2][4][2], const Unit& u, int wr, int wc, int fr, int fq) const {
;     ...
;             for (int m = 0; m < 4; ++m) { const int row = row0 + ai * HALF + m * 16; bf16_t* rowp = O + (size_t)row * ldc + col0; const float rs = rsv[ai][m];
; #pragma unroll
;                 for (int bj = 0; bj < 2; ++bj) { f32x4 v0 = acc[ai][bj][m][0] * rs, v1 = acc[ai][bj][m][1] * rs;
;                     if (ACT == 1) {
; #pragma unroll
;                         for (int j = 0; j < 4; ++j) { v0[j] = gelu_tanh(v0[j]); v1[j] = gelu_tanh(v1[j]); } }
;                     u32x4 w; w.x = cvt_pk_bf16(v0[0], v0[1]); w.y = cvt_pk_bf16(v0[2], v0[3]); w.z = cvt_pk_bf16(v1[0], v1[1]); w.w = cvt_pk_bf16(v1[2], v1[3]);
;                     *(u32x4*)(rowp + bj * HALF) = w; } }
; template <class Epi, bool ALIGN_EPI>
; __device__ __forceinline__ void gemm_phase(LAS unsigned char* lds, const Gemm g, const StaticOrder& S, const Epi& E, const int tid) {
;     ...
;             PG8_LDB(B0, 0, 0); PG8_LDB(B1, 0, 1); PG8_SCHED; PG8_LDA(At, 0, 0); PG8_STAGE(PG8_SA(1, 1), a1 + hA, voffA);
;             PG8_WAIT_V(8); PG8_WAIT_L(0); PG8_BAR; PG8_MMA(0, 0, At, B0); PG8_MMA(0, 1, At, B1); PG8_BAR; PG8_SCHED;
.Lq5_first_epi:
	s_add_i32 s11, s10, 2
	s_cmp_eq_u32 s55, s10
	s_cselect_b64 vcc, -1, 0
	v_add_u32_e32 v148, s33, v149
	s_add_i32 s10, 0, 0x14000
	ds_read_b128 v[152:155], v148
	ds_read_b128 v[156:159], v148 offset:1024
	ds_read_b128 v[160:163], v148 offset:2048
	ds_read_b128 v[164:167], v148 offset:3072
	v_add_u32_e32 v148, s10, v149
	ds_read_b128 v[176:179], v148
	ds_read_b128 v[180:183], v148 offset:1024
	ds_read_b128 v[184:187], v148 offset:2048
	ds_read_b128 v[188:191], v148 offset:3072
	v_lshl_add_u64 v[146:147], v[142:143], 0, s[92:93]
	v_cndmask_b32_e32 v147, v147, v139, vcc
	v_cndmask_b32_e32 v146, v146, v138, vcc
	v_cndmask_b32_e32 v221, v145, v141, vcc
	v_cndmask_b32_e32 v220, v144, v140, vcc
	v_lshl_add_u64 v[244:245], v[142:143], 0, v[134:135]
	s_add_i32 m0, s25, 0xc000
	ds_read_b128 v[192:195], v151
	ds_read_b128 v[196:199], v151 offset:1024
	ds_read_b128 v[200:203], v151 offset:2048
	ds_read_b128 v[204:207], v151 offset:3072
	ds_read_b128 v[208:211], v151 offset:4096
	ds_read_b128 v[212:215], v151 offset:5120
	ds_read_b128 v[216:219], v151 offset:6144
	ds_read_b128 v[240:243], v151 offset:7168
	global_load_lds_dwordx4 v[244:245], off
	v_lshl_add_u64 v[244:245], v[142:143], 0, v[136:137]
	s_add_i32 m0, s25, 0xe000
	s_nop 0
	global_load_lds_dwordx4 v[244:245], off
	s_waitcnt vmcnt(16)
	s_waitcnt lgkmcnt(0)
	s_barrier
	s_setprio 1
	s_waitcnt lgkmcnt(0)
	v_mfma_f32_16x16x32_bf16 v[124:127], v[152:155], v[192:195], 0
	s_lshl_b32 s98, s28, 5
	s_mov_b32 s99, 0
	v_mul_f32_e32 v60, v238, v60
	v_mul_f32_e32 v61, v238, v61
	v_mfma_f32_16x16x32_bf16 v[120:123], v[160:163], v[192:195], 0
	v_mul_f32_e32 v62, v238, v62
	v_mul_f32_e32 v63, v238, v63
	v_mul_f32_e32 v56, v238, v56
	v_mul_f32_e32 v57, v238, v57
	v_mfma_f32_16x16x32_bf16 v[108:111], v[152:155], v[200:203], 0
	v_mul_f32_e32 v58, v238, v58
	v_mul_f32_e32 v59, v238, v59
	v_cvt_pk_bf16_f32 v60, v60, v61
	v_cvt_pk_bf16_f32 v61, v62, v63
	v_mfma_f32_16x16x32_bf16 v[104:107], v[160:163], v[200:203], 0
	v_cvt_pk_bf16_f32 v62, v56, v57
	v_cvt_pk_bf16_f32 v63, v58, v59
	global_store_dwordx4 v[232:233], v[60:63], off
	v_mul_f32_e32 v52, v238, v52
	v_mfma_f32_16x16x32_bf16 v[92:95], v[152:155], v[208:211], 0
	v_mul_f32_e32 v53, v238, v53
	v_mul_f32_e32 v54, v238, v54
	v_mul_f32_e32 v55, v238, v55
	v_mul_f32_e32 v48, v238, v48
	v_mfma_f32_16x16x32_bf16 v[88:91], v[160:163], v[208:211], 0
	v_mul_f32_e32 v49, v238, v49
	v_mul_f32_e32 v50, v238, v50
	v_mul_f32_e32 v51, v238, v51
	v_cvt_pk_bf16_f32 v52, v52, v53
	v_mfma_f32_16x16x32_bf16 v[76:79], v[152:155], v[216:219], 0
	v_cvt_pk_bf16_f32 v53, v54, v55
	v_cvt_pk_bf16_f32 v54, v48, v49
	v_cvt_pk_bf16_f32 v55, v50, v51
	global_store_dwordx4 v[232:233], v[52:55], off offset:256
	v_mfma_f32_16x16x32_bf16 v[72:75], v[160:163], v[216:219], 0
	v_lshl_add_u64 v[232:233], v[232:233], 0, s[98:99]
	v_mul_f32_e32 v44, v239, v44
	v_mul_f32_e32 v45, v239, v45
	v_mul_f32_e32 v46, v239, v46
	v_mfma_f32_16x16x32_bf16 v[124:127], v[156:159], v[196:199], v[124:127]
	v_mul_f32_e32 v47, v239, v47
	v_mul_f32_e32 v40, v239, v40
	v_mul_f32_e32 v41, v239, v41
	v_mul_f32_e32 v42, v239, v42
	v_mfma_f32_16x16x32_bf16 v[120:123], v[164:167], v[196:199], v[120:123]
	v_mul_f32_e32 v43, v239, v43
	v_cvt_pk_bf16_f32 v44, v44, v45
	v_cvt_pk_bf16_f32 v45, v46, v47
	v_cvt_pk_bf16_f32 v46, v40, v41
	v_mfma_f32_16x16x32_bf16 v[108:111], v[156:159], v[204:207], v[108:111]
	v_cvt_pk_bf16_f32 v47, v42, v43
	global_store_dwordx4 v[232:233], v[44:47], off
	v_mul_f32_e32 v36, v239, v36
	v_mul_f32_e32 v37, v239, v37
	v_mfma_f32_16x16x32_bf16 v[104:107], v[164:167], v[204:207], v[104:107]
	v_mul_f32_e32 v38, v239, v38
	v_mul_f32_e32 v39, v239, v39
	v_mul_f32_e32 v32, v239, v32
	v_mul_f32_e32 v33, v239, v33
	v_mfma_f32_16x16x32_bf16 v[92:95], v[156:159], v[212:215], v[92:95]
	v_mul_f32_e32 v34, v239, v34
	v_mul_f32_e32 v35, v239, v35
	v_cvt_pk_bf16_f32 v36, v36, v37
	v_cvt_pk_bf16_f32 v37, v38, v39
	v_mfma_f32_16x16x32_bf16 v[88:91], v[164:167], v[212:215], v[88:91]
	v_cvt_pk_bf16_f32 v38, v32, v33
	v_cvt_pk_bf16_f32 v39, v34, v35
	global_store_dwordx4 v[232:233], v[36:39], off offset:256
	v_lshl_add_u64 v[232:233], v[232:233], 0, s[98:99]
	v_mfma_f32_16x16x32_bf16 v[76:79], v[156:159], v[240:243], v[76:79]
	v_mul_f32_e32 v28, v230, v28
	v_mul_f32_e32 v29, v230, v29
	v_mul_f32_e32 v30, v230, v30
	v_mul_f32_e32 v31, v230, v31
	v_mfma_f32_16x16x32_bf16 v[72:75], v[164:167], v[240:243], v[72:75]
	v_mul_f32_e32 v24, v230, v24
	v_mul_f32_e32 v25, v230, v25
	v_mul_f32_e32 v26, v230, v26
	v_mul_f32_e32 v27, v230, v27
	s_setprio 0
	s_setprio 1
	v_mfma_f32_16x16x32_bf16 v[116:119], v[176:179], v[192:195], 0
	v_cvt_pk_bf16_f32 v28, v28, v29
	v_cvt_pk_bf16_f32 v29, v30, v31
	v_cvt_pk_bf16_f32 v30, v24, v25
	v_cvt_pk_bf16_f32 v31, v26, v27
	v_mfma_f32_16x16x32_bf16 v[112:115], v[184:187], v[192:195], 0
	global_store_dwordx4 v[232:233], v[28:31], off
	v_mul_f32_e32 v20, v230, v20
	v_mul_f32_e32 v21, v230, v21
	v_mul_f32_e32 v22, v230, v22
	v_mfma_f32_16x16x32_bf16 v[100:103], v[176:179], v[200:203], 0
	v_mul_f32_e32 v23, v230, v23
	v_mul_f32_e32 v16, v230, v16
	v_mul_f32_e32 v17, v230, v17
	v_mul_f32_e32 v18, v230, v18
	v_mfma_f32_16x16x32_bf16 v[96:99], v[184:187], v[200:203], 0
	v_mul_f32_e32 v19, v230, v19
	v_cvt_pk_bf16_f32 v20, v20, v21
	v_cvt_pk_bf16_f32 v21, v22, v23
	v_cvt_pk_bf16_f32 v22, v16, v17
	v_mfma_f32_16x16x32_bf16 v[84:87], v[176:179], v[208:211], 0
	v_cvt_pk_bf16_f32 v23, v18, v19
	global_store_dwordx4 v[232:233], v[20:23], off offset:256
	v_lshl_add_u64 v[232:233], v[232:233], 0, s[98:99]
	v_mul_f32_e32 v12, v231, v12
	v_mfma_f32_16x16x32_bf16 v[80:83], v[184:187], v[208:211], 0
; #define PG8_STAGE(bufoff, gbase, voff) do { _Pragma("unroll") for (int _i = 0; _i < 2; ++_i) \
;         __builtin_amdgcn_global_load_lds((const unsigned*)((const char*)(gbase) + (voff)[_i]), (LAS unsigned*)(lds + (bufoff) + ldsw + _i * 8192), 16, 0, 0); } while (0)
; #define PG8_LDA(dst, b, h) do { _Pragma("unroll") for (int m = 0; m < 4; ++m) _Pragma("unroll") for (int k = 0; k < 2; ++k) dst[m][k] = *(const LAS bf16x8*)(lds + PG8_SA(b, h) + aoff + m * 2048 + k * 1024); } while (0)
; #define PG8_LDB(dst, b, h) do { _Pragma("unroll") for (int n = 0; n < 2; ++n) _Pragma("unroll") for (int k = 0; k < 2; ++k) dst[n][k] = *(const LAS bf16x8*)(lds + PG8_SB(b, h) + boff + n * 2048 + k * 1024); } while (0)
; #define PG8_MMA(ai, bj, At, Bt) do { __builtin_amdgcn_s_setprio(1); _Pragma("unroll") for (int k = 0; k < 2; ++k) _Pragma("unroll") for (int m = 0; m < 4; ++m) _Pragma("unroll") for (int n = 0; n < 2; ++n) \
;         acc[ai][bj][m][n] = __builtin_amdgcn_mfma_f32_16x16x32_bf16(Bt[n][k], At[m][k], acc[ai][bj][m][n], 0, 0, 0); __builtin_amdgcn_s_setprio(0); } while (0)
; #define PG8_WAIT_V(n) asm volatile("s_waitcnt vmcnt(" #n ")" ::: "memory")
; #define PG8_WAIT_L(n) asm volatile("s_waitcnt lgkmcnt(" #n ")" ::: "memory")
; #define PG8_BAR __builtin_amdgcn_s_barrier()
; #define PG8_SCHED __builtin_amdgcn_sched_barrier(0)
; template <class Epi, bool ALIGN_EPI>
; __device__ __forceinline__ void gemm_phase(LAS unsigned char* lds, const Gemm g, const StaticOrder& S, const Epi& E, const int tid) {
;     ...
;             PG8_LDB(B0, 0, 0); PG8_LDB(B1, 0, 1); PG8_SCHED; PG8_LDA(At, 0, 0); PG8_STAGE(PG8_SA(1, 1), a1 + hA, voffA);
;             PG8_WAIT_V(8); PG8_WAIT_L(0); PG8_BAR; PG8_MMA(0, 0, At, B0); PG8_MMA(0, 1, At, B1); PG8_BAR; PG8_SCHED;
;             PG8_LDA(At, 0, 1); PG8_STAGE(PG8_SB(0, 0), b2, voffB); PG8_STAGE(PG8_SB(0, 1), b2 + hB, voffB); PG8_STAGE(PG8_SA(0, 0), a2, voffA);
;             PG8_WAIT_V(8); PG8_WAIT_L(0); PG8_BAR; PG8_MMA(1, 0, At, B0); PG8_MMA(1, 1, At, B1); PG8_BAR; PG8_SCHED;
;             PG8_LDB(B0, 1, 0); PG8_LDB(B1, 1, 1); PG8_SCHED; PG8_LDA(At, 1, 0); PG8_STAGE(PG8_SA(0, 1), a2 + hA, voffA);
;             PG8_WAIT_V(8); PG8_WAIT_L(0); PG8_BAR; PG8_MMA(0, 0, At, B0); PG8_MMA(0, 1, At, B1); PG8_BAR; PG8_SCHED;
	v_mul_f32_e32 v13, v231, v13
	v_mul_f32_e32 v14, v231, v14
	v_mul_f32_e32 v15, v231, v15
	v_mul_f32_e32 v8, v231, v8
	v_mfma_f32_16x16x32_bf16 v[68:71], v[176:179], v[216:219], 0
	v_mul_f32_e32 v9, v231, v9
	v_mul_f32_e32 v10, v231, v10
	v_mul_f32_e32 v11, v231, v11
	v_cvt_pk_bf16_f32 v12, v12, v13
	v_mfma_f32_16x16x32_bf16 v[64:67], v[184:187], v[216:219], 0
	v_cvt_pk_bf16_f32 v13, v14, v15
	v_cvt_pk_bf16_f32 v14, v8, v9
	v_cvt_pk_bf16_f32 v15, v10, v11
	global_store_dwordx4 v[232:233], v[12:15], off
	v_mfma_f32_16x16x32_bf16 v[116:119], v[180:183], v[196:199], v[116:119]
	v_mul_f32_e32 v4, v231, v4
	v_mul_f32_e32 v5, v231, v5
	v_mul_f32_e32 v6, v231, v6
	v_mul_f32_e32 v7, v231, v7
	v_mfma_f32_16x16x32_bf16 v[112:115], v[188:191], v[196:199], v[112:115]
	v_mul_f32_e32 v0, v231, v0
	v_mul_f32_e32 v1, v231, v1
	v_mul_f32_e32 v2, v231, v2
	v_mul_f32_e32 v3, v231, v3
	v_mfma_f32_16x16x32_bf16 v[100:103], v[180:183], v[204:207], v[100:103]
	v_cvt_pk_bf16_f32 v4, v4, v5
	v_cvt_pk_bf16_f32 v5, v6, v7
	v_cvt_pk_bf16_f32 v6, v0, v1
	v_cvt_pk_bf16_f32 v7, v2, v3
	v_mfma_f32_16x16x32_bf16 v[96:99], v[188:191], v[204:207], v[96:99]
	global_store_dwordx4 v[232:233], v[4:7], off offset:256
	v_mfma_f32_16x16x32_bf16 v[84:87], v[180:183], v[212:215], v[84:87]
	v_mfma_f32_16x16x32_bf16 v[80:83], v[188:191], v[212:215], v[80:83]
	v_mfma_f32_16x16x32_bf16 v[68:71], v[180:183], v[240:243], v[68:71]
	v_mfma_f32_16x16x32_bf16 v[64:67], v[188:191], v[240:243], v[64:67]
	s_setprio 0
	s_barrier
	s_add_i32 s62, s33, s45
	v_lshl_add_u64 v[244:245], v[220:221], 0, v[168:169]
	s_mov_b32 m0, s62
	ds_read_b128 v[192:195], v151 offset:16384
	ds_read_b128 v[196:199], v151 offset:17408
	ds_read_b128 v[200:203], v151 offset:18432
	ds_read_b128 v[204:207], v151 offset:19456
	ds_read_b128 v[208:211], v151 offset:20480
	ds_read_b128 v[212:215], v151 offset:21504
	ds_read_b128 v[216:219], v151 offset:22528
	ds_read_b128 v[240:243], v151 offset:23552
	global_load_lds_dwordx4 v[244:245], off
	v_lshl_add_u64 v[246:247], v[220:221], 0, v[128:129]
	s_add_i32 m0, s62, 0x2000
	v_lshl_add_u64 v[220:221], v[220:221], 0, s[12:13]
	s_add_i32 s10, s10, s45
	global_load_lds_dwordx4 v[246:247], off
	v_lshl_add_u64 v[248:249], v[220:221], 0, v[168:169]
	s_mov_b32 m0, s10
	v_lshl_add_u64 v[220:221], v[220:221], 0, v[128:129]
	global_load_lds_dwordx4 v[248:249], off
	s_add_i32 m0, s10, 0x2000
	v_lshl_add_u64 v[250:251], v[146:147], 0, v[132:133]
	global_load_lds_dwordx4 v[220:221], off
	s_mov_b32 m0, s25
	v_lshl_add_u64 v[252:253], v[146:147], 0, v[130:131]
	global_load_lds_dwordx4 v[250:251], off
	s_mov_b32 m0, s50
	s_nop 0
	global_load_lds_dwordx4 v[252:253], off
	s_waitcnt vmcnt(24)
	s_waitcnt lgkmcnt(0)
	s_barrier
	s_setprio 1
	s_waitcnt lgkmcnt(0)
	v_mfma_f32_16x16x32_bf16 v[60:63], v[152:155], v[192:195], 0
	v_mfma_f32_16x16x32_bf16 v[56:59], v[160:163], v[192:195], 0
	v_mfma_f32_16x16x32_bf16 v[44:47], v[152:155], v[200:203], 0
	v_mfma_f32_16x16x32_bf16 v[40:43], v[160:163], v[200:203], 0
	v_mfma_f32_16x16x32_bf16 v[28:31], v[152:155], v[208:211], 0
	v_mfma_f32_16x16x32_bf16 v[24:27], v[160:163], v[208:211], 0
	v_mfma_f32_16x16x32_bf16 v[12:15], v[152:155], v[216:219], 0
	v_mfma_f32_16x16x32_bf16 v[8:11], v[160:163], v[216:219], 0
	v_mfma_f32_16x16x32_bf16 v[60:63], v[156:159], v[196:199], v[60:63]
	v_mfma_f32_16x16x32_bf16 v[56:59], v[164:167], v[196:199], v[56:59]
	v_mfma_f32_16x16x32_bf16 v[44:47], v[156:159], v[204:207], v[44:47]
	v_mfma_f32_16x16x32_bf16 v[40:43], v[164:167], v[204:207], v[40:43]
	v_mfma_f32_16x16x32_bf16 v[28:31], v[156:159], v[212:215], v[28:31]
	v_mfma_f32_16x16x32_bf16 v[24:27], v[164:167], v[212:215], v[24:27]
	v_mfma_f32_16x16x32_bf16 v[12:15], v[156:159], v[240:243], v[12:15]
	v_mfma_f32_16x16x32_bf16 v[8:11], v[164:167], v[240:243], v[8:11]
	s_setprio 0
	s_setprio 1
	v_mfma_f32_16x16x32_bf16 v[52:55], v[176:179], v[192:195], 0
	v_mfma_f32_16x16x32_bf16 v[48:51], v[184:187], v[192:195], 0
	v_mfma_f32_16x16x32_bf16 v[36:39], v[176:179], v[200:203], 0
	v_mfma_f32_16x16x32_bf16 v[32:35], v[184:187], v[200:203], 0
	v_mfma_f32_16x16x32_bf16 v[20:23], v[176:179], v[208:211], 0
	v_mfma_f32_16x16x32_bf16 v[16:19], v[184:187], v[208:211], 0
	v_mfma_f32_16x16x32_bf16 v[4:7], v[176:179], v[216:219], 0
	v_mfma_f32_16x16x32_bf16 v[0:3], v[184:187], v[216:219], 0
	v_mfma_f32_16x16x32_bf16 v[52:55], v[180:183], v[196:199], v[52:55]
	v_mfma_f32_16x16x32_bf16 v[48:51], v[188:191], v[196:199], v[48:51]
	v_mfma_f32_16x16x32_bf16 v[36:39], v[180:183], v[204:207], v[36:39]
	v_mfma_f32_16x16x32_bf16 v[32:35], v[188:191], v[204:207], v[32:35]
	v_mfma_f32_16x16x32_bf16 v[20:23], v[180:183], v[212:215], v[20:23]
	v_mfma_f32_16x16x32_bf16 v[16:19], v[188:191], v[212:215], v[16:19]
	v_mfma_f32_16x16x32_bf16 v[4:7], v[180:183], v[240:243], v[4:7]
	v_mfma_f32_16x16x32_bf16 v[0:3], v[188:191], v[240:243], v[0:3]
	s_setprio 0
	s_barrier
	s_add_i32 s10, 0, 0x18000
	v_add_u32_e32 v148, s10, v149
	s_add_i32 s62, 0, 0x1c000
	ds_read_b128 v[152:155], v148
	ds_read_b128 v[156:159], v148 offset:1024
	ds_read_b128 v[160:163], v148 offset:2048
	ds_read_b128 v[164:167], v148 offset:3072
	v_add_u32_e32 v148, s62, v149
	ds_read_b128 v[176:179], v148
	ds_read_b128 v[180:183], v148 offset:1024
	ds_read_b128 v[184:187], v148 offset:2048
	ds_read_b128 v[188:191], v148 offset:3072
	v_lshl_add_u64 v[146:147], v[146:147], 0, s[94:95]
	s_mov_b32 m0, s51
	v_lshl_add_u64 v[226:227], v[146:147], 0, v[132:133]
	ds_read_b128 v[192:195], v151 offset:32768
	ds_read_b128 v[196:199], v151 offset:33792
	ds_read_b128 v[200:203], v151 offset:34816
	ds_read_b128 v[204:207], v151 offset:35840
	ds_read_b128 v[208:211], v151 offset:36864
	ds_read_b128 v[212:215], v151 offset:37888
	ds_read_b128 v[216:219], v151 offset:38912
	ds_read_b128 v[240:243], v151 offset:39936
	global_load_lds_dwordx4 v[226:227], off
	v_lshl_add_u64 v[146:147], v[146:147], 0, v[130:131]
	s_mov_b32 m0, s52
	s_nop 0
	global_load_lds_dwordx4 v[146:147], off
	s_waitcnt vmcnt(16)
	s_waitcnt lgkmcnt(0)
	s_barrier
; #define PG8_STAGE(bufoff, gbase, voff) do { _Pragma("unroll") for (int _i = 0; _i < 2; ++_i) \
;         __builtin_amdgcn_global_load_lds((const unsigned*)((const char*)(gbase) + (voff)[_i]), (LAS unsigned*)(lds + (bufoff) + ldsw + _i * 8192), 16, 0, 0); } while (0)
; #define PG8_LDA(dst, b, h) do { _Pragma("unroll") for (int m = 0; m < 4; ++m) _Pragma("unroll") for (int k = 0; k < 2; ++k) dst[m][k] = *(const LAS bf16x8*)(lds + PG8_SA(b, h) + aoff + m * 2048 + k * 1024); } while (0)
; #define PG8_MMA(ai, bj, At, Bt) do { __builtin_amdgcn_s_setprio(1); _Pragma("unroll") for (int k = 0; k < 2; ++k) _Pragma("unroll") for (int m = 0; m < 4; ++m) _Pragma("unroll") for (int n = 0; n < 2; ++n) \
;         acc[ai][bj][m][n] = __builtin_amdgcn_mfma_f32_16x16x32_bf16(Bt[n][k], At[m][k], acc[ai][bj][m][n], 0, 0, 0); __builtin_amdgcn_s_setprio(0); } while (0)
; #define PG8_WAIT_V(n) asm volatile("s_waitcnt vmcnt(" #n ")" ::: "memory")
; #define PG8_WAIT_L(n) asm volatile("s_waitcnt lgkmcnt(" #n ")" ::: "memory")
; #define PG8_BAR __builtin_amdgcn_s_barrier()
; #define PG8_SCHED __builtin_amdgcn_sched_barrier(0)
; template <class Epi, bool ALIGN_EPI>
; __device__ __forceinline__ void gemm_phase(LAS unsigned char* lds, const Gemm g, const StaticOrder& S, const Epi& E, const int tid) {
;     ...
;             PG8_WAIT_V(8); PG8_WAIT_L(0); PG8_BAR; PG8_MMA(0, 0, At, B0); PG8_MMA(0, 1, At, B1); PG8_BAR; PG8_SCHED;
;             PG8_LDA(At, 1, 1); PG8_STAGE(PG8_SB(1, 0), b3, voffB); PG8_STAGE(PG8_SB(1, 1), b3 + hB, voffB); PG8_STAGE(PG8_SA(1, 0), a3, voffA);
;             PG8_WAIT_V(8); PG8_WAIT_L(0); PG8_BAR; PG8_MMA(1, 0, At, B0); PG8_MMA(1, 1, At, B1); PG8_BAR; PG8_SCHED;
;         }
	s_setprio 1
	s_waitcnt lgkmcnt(0)
	v_mfma_f32_16x16x32_bf16 v[124:127], v[152:155], v[192:195], v[124:127]
	v_mfma_f32_16x16x32_bf16 v[120:123], v[160:163], v[192:195], v[120:123]
	v_mfma_f32_16x16x32_bf16 v[108:111], v[152:155], v[200:203], v[108:111]
	v_mfma_f32_16x16x32_bf16 v[104:107], v[160:163], v[200:203], v[104:107]
	v_mfma_f32_16x16x32_bf16 v[92:95], v[152:155], v[208:211], v[92:95]
	v_mfma_f32_16x16x32_bf16 v[88:91], v[160:163], v[208:211], v[88:91]
	v_mfma_f32_16x16x32_bf16 v[76:79], v[152:155], v[216:219], v[76:79]
	v_mfma_f32_16x16x32_bf16 v[72:75], v[160:163], v[216:219], v[72:75]
	v_mfma_f32_16x16x32_bf16 v[124:127], v[156:159], v[196:199], v[124:127]
	v_mfma_f32_16x16x32_bf16 v[120:123], v[164:167], v[196:199], v[120:123]
	v_mfma_f32_16x16x32_bf16 v[108:111], v[156:159], v[204:207], v[108:111]
	v_mfma_f32_16x16x32_bf16 v[104:107], v[164:167], v[204:207], v[104:107]
	v_mfma_f32_16x16x32_bf16 v[92:95], v[156:159], v[212:215], v[92:95]
	v_mfma_f32_16x16x32_bf16 v[88:91], v[164:167], v[212:215], v[88:91]
	v_mfma_f32_16x16x32_bf16 v[76:79], v[156:159], v[240:243], v[76:79]
	v_mfma_f32_16x16x32_bf16 v[72:75], v[164:167], v[240:243], v[72:75]
	s_setprio 0
	s_setprio 1
	v_mfma_f32_16x16x32_bf16 v[116:119], v[176:179], v[192:195], v[116:119]
	v_mfma_f32_16x16x32_bf16 v[112:115], v[184:187], v[192:195], v[112:115]
	v_mfma_f32_16x16x32_bf16 v[100:103], v[176:179], v[200:203], v[100:103]
	v_mfma_f32_16x16x32_bf16 v[96:99], v[184:187], v[200:203], v[96:99]
	v_mfma_f32_16x16x32_bf16 v[84:87], v[176:179], v[208:211], v[84:87]
	v_mfma_f32_16x16x32_bf16 v[80:83], v[184:187], v[208:211], v[80:83]
	v_mfma_f32_16x16x32_bf16 v[68:71], v[176:179], v[216:219], v[68:71]
	v_mfma_f32_16x16x32_bf16 v[64:67], v[184:187], v[216:219], v[64:67]
	v_mfma_f32_16x16x32_bf16 v[116:119], v[180:183], v[196:199], v[116:119]
	v_mfma_f32_16x16x32_bf16 v[112:115], v[188:191], v[196:199], v[112:115]
	v_mfma_f32_16x16x32_bf16 v[100:103], v[180:183], v[204:207], v[100:103]
	v_mfma_f32_16x16x32_bf16 v[96:99], v[188:191], v[204:207], v[96:99]
	v_mfma_f32_16x16x32_bf16 v[84:87], v[180:183], v[212:215], v[84:87]
	v_mfma_f32_16x16x32_bf16 v[80:83], v[188:191], v[212:215], v[80:83]
	v_mfma_f32_16x16x32_bf16 v[68:71], v[180:183], v[240:243], v[68:71]
	v_mfma_f32_16x16x32_bf16 v[64:67], v[188:191], v[240:243], v[64:67]
	s_setprio 0
	s_barrier
	s_add_i32 s10, s10, s45
	v_lshl_add_u64 v[146:147], v[244:245], 0, s[92:93]
	s_mov_b32 m0, s10
	ds_read_b128 v[192:195], v151 offset:49152
	ds_read_b128 v[196:199], v151 offset:50176
	ds_read_b128 v[200:203], v151 offset:51200
	ds_read_b128 v[204:207], v151 offset:52224
	ds_read_b128 v[208:211], v151 offset:53248
	ds_read_b128 v[212:215], v151 offset:54272
	ds_read_b128 v[216:219], v151 offset:55296
	ds_read_b128 v[240:243], v151 offset:56320
	global_load_lds_dwordx4 v[146:147], off
	v_lshl_add_u64 v[146:147], v[246:247], 0, s[92:93]
	s_add_i32 m0, s10, 0x2000
	s_add_i32 s10, s62, s45
	global_load_lds_dwordx4 v[146:147], off
	v_lshl_add_u64 v[146:147], v[248:249], 0, s[92:93]
	s_mov_b32 m0, s10
	s_nop 0
	global_load_lds_dwordx4 v[146:147], off
	v_lshl_add_u64 v[146:147], v[220:221], 0, s[92:93]
	s_add_i32 m0, s10, 0x2000
	s_nop 0
	global_load_lds_dwordx4 v[146:147], off
	v_lshl_add_u64 v[146:147], v[250:251], 0, s[92:93]
	s_mov_b32 m0, s53
	s_nop 0
	global_load_lds_dwordx4 v[146:147], off
	v_lshl_add_u64 v[146:147], v[252:253], 0, s[92:93]
	s_mov_b32 m0, s54
	s_nop 0
	global_load_lds_dwordx4 v[146:147], off
	s_waitcnt vmcnt(8)
	s_waitcnt lgkmcnt(0)
	s_barrier
	s_setprio 1
	s_waitcnt lgkmcnt(0)
	v_mfma_f32_16x16x32_bf16 v[60:63], v[152:155], v[192:195], v[60:63]
	v_mfma_f32_16x16x32_bf16 v[56:59], v[160:163], v[192:195], v[56:59]
	v_mfma_f32_16x16x32_bf16 v[44:47], v[152:155], v[200:203], v[44:47]
	v_mfma_f32_16x16x32_bf16 v[40:43], v[160:163], v[200:203], v[40:43]
	v_mfma_f32_16x16x32_bf16 v[28:31], v[152:155], v[208:211], v[28:31]
	v_mfma_f32_16x16x32_bf16 v[24:27], v[160:163], v[208:211], v[24:27]
	v_mfma_f32_16x16x32_bf16 v[12:15], v[152:155], v[216:219], v[12:15]
	v_mfma_f32_16x16x32_bf16 v[8:11], v[160:163], v[216:219], v[8:11]
	v_mfma_f32_16x16x32_bf16 v[60:63], v[156:159], v[196:199], v[60:63]
	v_mfma_f32_16x16x32_bf16 v[56:59], v[164:167], v[196:199], v[56:59]
	v_mfma_f32_16x16x32_bf16 v[44:47], v[156:159], v[204:207], v[44:47]
	v_mfma_f32_16x16x32_bf16 v[40:43], v[164:167], v[204:207], v[40:43]
	v_mfma_f32_16x16x32_bf16 v[28:31], v[156:159], v[212:215], v[28:31]
	v_mfma_f32_16x16x32_bf16 v[24:27], v[164:167], v[212:215], v[24:27]
	v_mfma_f32_16x16x32_bf16 v[12:15], v[156:159], v[240:243], v[12:15]
	v_mfma_f32_16x16x32_bf16 v[8:11], v[164:167], v[240:243], v[8:11]
	s_setprio 0
	s_setprio 1
	v_mfma_f32_16x16x32_bf16 v[52:55], v[176:179], v[192:195], v[52:55]
	v_mfma_f32_16x16x32_bf16 v[48:51], v[184:187], v[192:195], v[48:51]
	v_mfma_f32_16x16x32_bf16 v[36:39], v[176:179], v[200:203], v[36:39]
	v_mfma_f32_16x16x32_bf16 v[32:35], v[184:187], v[200:203], v[32:35]
	v_mfma_f32_16x16x32_bf16 v[20:23], v[176:179], v[208:211], v[20:23]
	v_mfma_f32_16x16x32_bf16 v[16:19], v[184:187], v[208:211], v[16:19]
	v_mfma_f32_16x16x32_bf16 v[4:7], v[176:179], v[216:219], v[4:7]
	v_mfma_f32_16x16x32_bf16 v[0:3], v[184:187], v[216:219], v[0:3]
	v_mfma_f32_16x16x32_bf16 v[52:55], v[180:183], v[196:199], v[52:55]
	v_mfma_f32_16x16x32_bf16 v[48:51], v[188:191], v[196:199], v[48:51]
	v_mfma_f32_16x16x32_bf16 v[36:39], v[180:183], v[204:207], v[36:39]
	v_mfma_f32_16x16x32_bf16 v[32:35], v[188:191], v[204:207], v[32:35]
	v_mfma_f32_16x16x32_bf16 v[20:23], v[180:183], v[212:215], v[20:23]
	v_mfma_f32_16x16x32_bf16 v[16:19], v[188:191], v[212:215], v[16:19]
	v_mfma_f32_16x16x32_bf16 v[4:7], v[180:183], v[240:243], v[4:7]
	v_mfma_f32_16x16x32_bf16 v[0:3], v[188:191], v[240:243], v[0:3]
	s_setprio 0
	s_barrier
	v_lshl_add_u64 v[142:143], v[142:143], 0, s[80:81]
	v_lshl_add_u64 v[144:145], v[144:145], 0, s[80:81]
	s_mov_b32 s10, s11
	s_cmp_eq_u32 s10, s55
	s_cbranch_scc1 .Lq5_last
	s_branch .LBB0_354
